# candidateA_plus_rglru_hin_chain_batched_reads
# speedup vs baseline: 1.0002x; 1.0002x over previous
; DEVI float sigmoidf_(float x) { return __builtin_amdgcn_rcpf(1.0f + __builtin_amdgcn_exp2f(-x * LOG2E)); }
; #define MFMA(a, b, c) __builtin_amdgcn_mfma_f32_16x16x32_bf16((a), (b), (c), 0, 0, 0)
; __device__ __forceinline__ void rglru_item8(const Params& p, unsigned char* lds, int item) {
;     ...
;       for (int kk = 0; kk < 4; ++kk) { const bf16x8 ax = *(const bf16x8*)(xcA + (16 * tt + fr) * 136 + 32 * kk + 8 * fq);
; #pragma unroll
;         for (int nt = 0; nt < 2; ++nt) { R[nt] = MFMA(ax, wa[nt][kk], R[nt]); I[nt] = MFMA(ax, wx[nt][kk], I[nt]); } }
; #pragma unroll
;       for (int nt = 0; nt < 2; ++nt)
; #pragma unroll
;         for (int r = 0; r < 4; ++r) {
;           const int t = 16 * tt + 4 * fq + r, jl = jh * 32 + 16 * nt + fr;
;           const float rg = sigmoidf_(R[nt][r] + ba[nt]), ig = sigmoidf_(I[nt][r] + bx[nt]);
;           const float la = -8.0f * rg * sp[nt];
;           aS[t * 65 + jl] = __builtin_amdgcn_exp2f(la * LOG2E);
;           const float x2 = 2.0f * la, om = x2 > -0.25f ? neg_expm1_small(x2) : 1.0f - __builtin_amdgcn_exp2f(x2 * LOG2E);
;           uS[t * 65 + jl] = __builtin_amdgcn_sqrtf(om) * (ig * xcF[t * 65 + jl]);
;         }
.LBB0_555:
	ds_read_b128 v[80:83], v103 offset:18224
	ds_read_b128 v[104:107], v103 offset:18288
	s_waitcnt lgkmcnt(1)
	v_mfma_f32_16x16x32_bf16 v[84:87], v[80:83], v[0:3], 0
	v_mfma_f32_16x16x32_bf16 v[88:91], v[80:83], v[8:11], 0
	v_mfma_f32_16x16x32_bf16 v[92:95], v[80:83], v[32:35], 0
	v_mfma_f32_16x16x32_bf16 v[80:83], v[80:83], v[40:43], 0
	s_waitcnt lgkmcnt(0)
	v_mfma_f32_16x16x32_bf16 v[84:87], v[104:107], v[4:7], v[84:87]
	v_mfma_f32_16x16x32_bf16 v[88:91], v[104:107], v[12:15], v[88:91]
	v_mfma_f32_16x16x32_bf16 v[92:95], v[104:107], v[36:39], v[92:95]
	v_mfma_f32_16x16x32_bf16 v[80:83], v[104:107], v[44:47], v[80:83]
	ds_read_b128 v[104:107], v103 offset:18352
	s_waitcnt lgkmcnt(0)
	v_mfma_f32_16x16x32_bf16 v[84:87], v[104:107], v[16:19], v[84:87]
	v_mfma_f32_16x16x32_bf16 v[88:91], v[104:107], v[24:27], v[88:91]
	v_mfma_f32_16x16x32_bf16 v[182:185], v[104:107], v[48:51], v[92:95]
	v_mfma_f32_16x16x32_bf16 v[80:83], v[104:107], v[56:59], v[80:83]
	ds_read_b128 v[104:107], v103 offset:18416
	s_waitcnt lgkmcnt(0)
	v_mfma_f32_16x16x32_bf16 v[92:95], v[104:107], v[20:23], v[84:87]
	s_nop 7
	v_add_f32_e32 v92, v116, v92
	v_mul_f32_e32 v92, 0xbfb8aa3b, v92
	v_exp_f32_e32 v92, v92
	v_mfma_f32_16x16x32_bf16 v[88:91], v[104:107], v[28:31], v[88:91]
	v_add_f32_e32 v92, 1.0, v92
	v_rcp_f32_e32 v92, v92
	v_mfma_f32_16x16x32_bf16 v[84:87], v[104:107], v[52:55], v[182:185]
	v_mul_f32_e32 v92, 0xc1000000, v92
	v_mul_f32_e32 v92, v137, v92
	v_mul_f32_e32 v97, 0x3fb8aa3b, v92
	v_exp_f32_e32 v97, v97
	v_mfma_f32_16x16x32_bf16 v[80:83], v[104:107], v[60:63], v[80:83]
	ds_write_b32 v145, v97 offset:52272
	v_add_f32_e32 v97, v92, v92
	v_cmp_nlt_f32_e32 vcc, s65, v97
	s_and_saveexec_b64 s[6:7], vcc
	s_xor_b64 s[6:7], exec, s[6:7]
	v_mul_f32_e32 v92, 0x3fb8aa3b, v97
	v_exp_f32_e32 v92, v92
	s_nop 0
	v_sub_f32_e32 v92, 1.0, v92
	s_andn2_saveexec_b64 s[6:7], s[6:7]
	v_fmamk_f32 v92, v97, 0x39500d01, v101
	v_fmaak_f32 v92, v97, v92, 0x3c088889
	v_fmaak_f32 v92, v97, v92, 0x3d2aaaab
	v_fmaak_f32 v92, v97, v92, 0x3e2aaaab
	v_fma_f32 v92, v97, v92, 0.5
	v_fma_f32 v92, v97, v92, 1.0
	v_mul_f32_e64 v92, v92, -v97
	s_or_b64 exec, exec, s[6:7]
	v_add_f32_e32 v88, v118, v88
	v_mul_f32_e32 v88, 0xbfb8aa3b, v88
	v_exp_f32_e32 v88, v88
	ds_read_b32 v97, v145 offset:35632
	v_sqrt_f32_e32 v92, v92
	v_add_f32_e32 v88, 1.0, v88
	v_rcp_f32_e32 v88, v88
	s_waitcnt lgkmcnt(0)
	v_mul_f32_e32 v88, v88, v97
	v_mul_f32_e32 v88, v92, v88
	ds_write_b32 v146, v88
	v_add_f32_e32 v88, v116, v93
	v_mul_f32_e32 v88, 0xbfb8aa3b, v88
	v_exp_f32_e32 v88, v88
	s_nop 0
	v_add_f32_e32 v88, 1.0, v88
	v_rcp_f32_e32 v88, v88
	s_nop 0
	v_mul_f32_e32 v88, 0xc1000000, v88
	v_mul_f32_e32 v88, v137, v88
	v_mul_f32_e32 v92, 0x3fb8aa3b, v88
	v_exp_f32_e32 v92, v92
	ds_write_b32 v145, v92 offset:52532
	v_add_f32_e32 v92, v88, v88
	v_cmp_nlt_f32_e32 vcc, s65, v92
	s_and_saveexec_b64 s[6:7], vcc
	s_xor_b64 s[6:7], exec, s[6:7]
	v_mul_f32_e32 v88, 0x3fb8aa3b, v92
	v_exp_f32_e32 v88, v88
	s_nop 0
	v_sub_f32_e32 v88, 1.0, v88
	s_andn2_saveexec_b64 s[6:7], s[6:7]
	v_fmamk_f32 v88, v92, 0x39500d01, v101
	v_fmaak_f32 v88, v92, v88, 0x3c088889
	v_fmaak_f32 v88, v92, v88, 0x3d2aaaab
	v_fmaak_f32 v88, v92, v88, 0x3e2aaaab
	v_fma_f32 v88, v92, v88, 0.5
	v_fma_f32 v88, v92, v88, 1.0
	v_mul_f32_e64 v88, v88, -v92
	s_or_b64 exec, exec, s[6:7]
	v_add_f32_e32 v89, v118, v89
	v_mul_f32_e32 v89, 0xbfb8aa3b, v89
	v_exp_f32_e32 v89, v89
	ds_read_b32 v92, v145 offset:35892
	v_sqrt_f32_e32 v88, v88
	v_add_f32_e32 v89, 1.0, v89
	v_rcp_f32_e32 v89, v89
	s_waitcnt lgkmcnt(0)
	v_mul_f32_e32 v89, v89, v92
	v_mul_f32_e32 v88, v88, v89
	ds_write_b32 v147, v88
	v_add_f32_e32 v88, v116, v94
	v_mul_f32_e32 v88, 0xbfb8aa3b, v88
	v_exp_f32_e32 v88, v88
	s_nop 0
	v_add_f32_e32 v88, 1.0, v88
	v_rcp_f32_e32 v88, v88
	s_nop 0
	v_mul_f32_e32 v88, 0xc1000000, v88
	v_mul_f32_e32 v88, v137, v88
	v_mul_f32_e32 v89, 0x3fb8aa3b, v88
	v_exp_f32_e32 v89, v89
	ds_write_b32 v145, v89 offset:52792
	v_add_f32_e32 v89, v88, v88
	v_cmp_nlt_f32_e32 vcc, s65, v89
	s_and_saveexec_b64 s[6:7], vcc
	s_xor_b64 s[6:7], exec, s[6:7]
	v_mul_f32_e32 v88, 0x3fb8aa3b, v89
	v_exp_f32_e32 v88, v88
	s_nop 0
	v_sub_f32_e32 v88, 1.0, v88
	s_andn2_saveexec_b64 s[6:7], s[6:7]
	v_fmamk_f32 v88, v89, 0x39500d01, v101
	v_fmaak_f32 v88, v89, v88, 0x3c088889
	v_fmaak_f32 v88, v89, v88, 0x3d2aaaab
	v_fmaak_f32 v88, v89, v88, 0x3e2aaaab
	v_fma_f32 v88, v89, v88, 0.5
	v_fma_f32 v88, v89, v88, 1.0
	v_mul_f32_e64 v88, v88, -v89
	s_or_b64 exec, exec, s[6:7]
	v_add_f32_e32 v89, v118, v90
	v_mul_f32_e32 v89, 0xbfb8aa3b, v89
	v_exp_f32_e32 v89, v89
	ds_read_b32 v90, v145 offset:36152
	v_sqrt_f32_e32 v88, v88
	v_add_f32_e32 v89, 1.0, v89
	v_rcp_f32_e32 v89, v89
	s_waitcnt lgkmcnt(0)
	v_mul_f32_e32 v89, v89, v90
	v_mul_f32_e32 v88, v88, v89
	ds_write_b32 v148, v88
	v_add_f32_e32 v88, v116, v95
	v_mul_f32_e32 v88, 0xbfb8aa3b, v88
	v_exp_f32_e32 v88, v88
	s_nop 0
	v_add_f32_e32 v88, 1.0, v88
	v_rcp_f32_e32 v88, v88
	s_nop 0
	v_mul_f32_e32 v88, 0xc1000000, v88
	v_mul_f32_e32 v88, v137, v88
	v_mul_f32_e32 v89, 0x3fb8aa3b, v88
	v_exp_f32_e32 v89, v89
	ds_write_b32 v145, v89 offset:53052
	v_add_f32_e32 v89, v88, v88
	v_cmp_nlt_f32_e32 vcc, s65, v89
	s_and_saveexec_b64 s[6:7], vcc
	s_xor_b64 s[6:7], exec, s[6:7]
	v_mul_f32_e32 v88, 0x3fb8aa3b, v89
	v_exp_f32_e32 v88, v88
	s_nop 0
	v_sub_f32_e32 v88, 1.0, v88
	s_andn2_saveexec_b64 s[6:7], s[6:7]
	v_fmamk_f32 v88, v89, 0x39500d01, v101
	v_fmaak_f32 v88, v89, v88, 0x3c088889
	v_fmaak_f32 v88, v89, v88, 0x3d2aaaab
	v_fmaak_f32 v88, v89, v88, 0x3e2aaaab
	v_fma_f32 v88, v89, v88, 0.5
	v_fma_f32 v88, v89, v88, 1.0
	v_mul_f32_e64 v88, v88, -v89
	s_or_b64 exec, exec, s[6:7]
	v_add_f32_e32 v89, v118, v91
	v_add_f32_e32 v84, v117, v84
	v_mul_f32_e32 v89, 0xbfb8aa3b, v89
	v_mul_f32_e32 v84, 0xbfb8aa3b, v84
	v_exp_f32_e32 v89, v89
	v_exp_f32_e32 v84, v84
	ds_read_b32 v90, v145 offset:36412
	v_sqrt_f32_e32 v88, v88
	v_add_f32_e32 v89, 1.0, v89
	v_add_f32_e32 v84, 1.0, v84
	v_rcp_f32_e32 v89, v89
	v_rcp_f32_e32 v84, v84
	s_waitcnt lgkmcnt(0)
; DEVI float sigmoidf_(float x) { return __builtin_amdgcn_rcpf(1.0f + __builtin_amdgcn_exp2f(-x * LOG2E)); }
; #define LBAR() do { asm volatile("s_waitcnt lgkmcnt(0)" ::: "memory"); __builtin_amdgcn_s_barrier(); asm volatile("" ::: "memory"); } while (0)
; __device__ __forceinline__ void rglru_item8(const Params& p, unsigned char* lds, int item) {
;     ...
;         for (int r = 0; r < 4; ++r) {
;           const int t = 16 * tt + 4 * fq + r, jl = jh * 32 + 16 * nt + fr;
;           const float rg = sigmoidf_(R[nt][r] + ba[nt]), ig = sigmoidf_(I[nt][r] + bx[nt]);
;           const float la = -8.0f * rg * sp[nt];
;           aS[t * 65 + jl] = __builtin_amdgcn_exp2f(la * LOG2E);
;           const float x2 = 2.0f * la, om = x2 > -0.25f ? neg_expm1_small(x2) : 1.0f - __builtin_amdgcn_exp2f(x2 * LOG2E);
;           uS[t * 65 + jl] = __builtin_amdgcn_sqrtf(om) * (ig * xcF[t * 65 + jl]);
;         }
;     }
;     LBAR();
;     const int j = lane, seg = w;
;     float Lk[8], Pk[8];
;     { float P = 1.f, L = 0.f;
; #pragma unroll
;       for (int k = 0; k < 8; ++k) { const float a = aS[(8 * seg + k) * 65 + j], u = uS[(8 * seg + k) * 65 + j]; L = a * L + u; P = a * P; Lk[k] = L; Pk[k] = P; }
;       segP[seg * 64 + j] = P; segL[seg * 64 + j] = L; }
;     LBAR();
;     { float hin = hst[cur * 64 + j];
; #pragma unroll
;       for (int sI = 0; sI < 7; ++sI) if (sI < seg) hin = segP[sI * 64 + j] * hin + segL[sI * 64 + j];
	v_mul_f32_e32 v89, v89, v90
	v_mul_f32_e32 v84, 0xc1000000, v84
	v_mul_f32_e32 v88, v88, v89
	v_mul_f32_e32 v84, v139, v84
	ds_write_b32 v149, v88
	v_mul_f32_e32 v88, 0x3fb8aa3b, v84
	v_exp_f32_e32 v88, v88
	ds_write_b32 v145, v88 offset:52336
	v_add_f32_e32 v88, v84, v84
	v_cmp_nlt_f32_e32 vcc, s65, v88
	s_and_saveexec_b64 s[6:7], vcc
	s_xor_b64 s[6:7], exec, s[6:7]
	v_mul_f32_e32 v84, 0x3fb8aa3b, v88
	v_exp_f32_e32 v84, v84
	s_nop 0
	v_sub_f32_e32 v84, 1.0, v84
	s_andn2_saveexec_b64 s[6:7], s[6:7]
	v_fmamk_f32 v84, v88, 0x39500d01, v101
	v_fmaak_f32 v84, v88, v84, 0x3c088889
	v_fmaak_f32 v84, v88, v84, 0x3d2aaaab
	v_fmaak_f32 v84, v88, v84, 0x3e2aaaab
	v_fma_f32 v84, v88, v84, 0.5
	v_fma_f32 v84, v88, v84, 1.0
	v_mul_f32_e64 v84, v84, -v88
	s_or_b64 exec, exec, s[6:7]
	v_add_f32_e32 v80, v119, v80
	v_mul_f32_e32 v80, 0xbfb8aa3b, v80
	v_exp_f32_e32 v80, v80
	ds_read_b32 v88, v145 offset:35696
	v_sqrt_f32_e32 v84, v84
	v_add_f32_e32 v80, 1.0, v80
	v_rcp_f32_e32 v80, v80
	s_waitcnt lgkmcnt(0)
	v_mul_f32_e32 v80, v80, v88
	v_mul_f32_e32 v80, v84, v80
	ds_write_b32 v151, v80
	v_add_f32_e32 v80, v117, v85
	v_mul_f32_e32 v80, 0xbfb8aa3b, v80
	v_exp_f32_e32 v80, v80
	s_nop 0
	v_add_f32_e32 v80, 1.0, v80
	v_rcp_f32_e32 v80, v80
	s_nop 0
	v_mul_f32_e32 v80, 0xc1000000, v80
	v_mul_f32_e32 v80, v139, v80
	v_mul_f32_e32 v84, 0x3fb8aa3b, v80
	v_exp_f32_e32 v84, v84
	ds_write_b32 v150, v84 offset:52532
	v_add_f32_e32 v84, v80, v80
	v_cmp_nlt_f32_e32 vcc, s65, v84
	s_and_saveexec_b64 s[6:7], vcc
	s_xor_b64 s[6:7], exec, s[6:7]
	v_mul_f32_e32 v80, 0x3fb8aa3b, v84
	v_exp_f32_e32 v80, v80
	s_nop 0
	v_sub_f32_e32 v80, 1.0, v80
	s_andn2_saveexec_b64 s[6:7], s[6:7]
	v_fmamk_f32 v80, v84, 0x39500d01, v101
	v_fmaak_f32 v80, v84, v80, 0x3c088889
	v_fmaak_f32 v80, v84, v80, 0x3d2aaaab
	v_fmaak_f32 v80, v84, v80, 0x3e2aaaab
	v_fma_f32 v80, v84, v80, 0.5
	v_fma_f32 v80, v84, v80, 1.0
	v_mul_f32_e64 v80, v80, -v84
	s_or_b64 exec, exec, s[6:7]
	v_add_f32_e32 v81, v119, v81
	v_mul_f32_e32 v81, 0xbfb8aa3b, v81
	v_exp_f32_e32 v81, v81
	ds_read_b32 v84, v150 offset:35892
	v_sqrt_f32_e32 v80, v80
	v_add_f32_e32 v81, 1.0, v81
	v_rcp_f32_e32 v81, v81
	s_waitcnt lgkmcnt(0)
	v_mul_f32_e32 v81, v81, v84
	v_mul_f32_e32 v80, v80, v81
	ds_write_b32 v152, v80
	v_add_f32_e32 v80, v117, v86
	v_mul_f32_e32 v80, 0xbfb8aa3b, v80
	v_exp_f32_e32 v80, v80
	s_nop 0
	v_add_f32_e32 v80, 1.0, v80
	v_rcp_f32_e32 v80, v80
	s_nop 0
	v_mul_f32_e32 v80, 0xc1000000, v80
	v_mul_f32_e32 v80, v139, v80
	v_mul_f32_e32 v81, 0x3fb8aa3b, v80
	v_exp_f32_e32 v81, v81
	ds_write_b32 v150, v81 offset:52792
	v_add_f32_e32 v81, v80, v80
	v_cmp_nlt_f32_e32 vcc, s65, v81
	s_and_saveexec_b64 s[6:7], vcc
	s_xor_b64 s[6:7], exec, s[6:7]
	v_mul_f32_e32 v80, 0x3fb8aa3b, v81
	v_exp_f32_e32 v80, v80
	s_nop 0
	v_sub_f32_e32 v80, 1.0, v80
	s_andn2_saveexec_b64 s[6:7], s[6:7]
	v_fmamk_f32 v80, v81, 0x39500d01, v101
	v_fmaak_f32 v80, v81, v80, 0x3c088889
	v_fmaak_f32 v80, v81, v80, 0x3d2aaaab
	v_fmaak_f32 v80, v81, v80, 0x3e2aaaab
	v_fma_f32 v80, v81, v80, 0.5
	v_fma_f32 v80, v81, v80, 1.0
	v_mul_f32_e64 v80, v80, -v81
	s_or_b64 exec, exec, s[6:7]
	v_add_f32_e32 v81, v119, v82
	v_mul_f32_e32 v81, 0xbfb8aa3b, v81
	v_exp_f32_e32 v81, v81
	ds_read_b32 v82, v150 offset:36152
	v_sqrt_f32_e32 v80, v80
	v_add_f32_e32 v81, 1.0, v81
	v_rcp_f32_e32 v81, v81
	s_waitcnt lgkmcnt(0)
	v_mul_f32_e32 v81, v81, v82
	v_mul_f32_e32 v80, v80, v81
	ds_write_b32 v153, v80
	v_add_f32_e32 v80, v117, v87
	v_mul_f32_e32 v80, 0xbfb8aa3b, v80
	v_exp_f32_e32 v80, v80
	s_nop 0
	v_add_f32_e32 v80, 1.0, v80
	v_rcp_f32_e32 v80, v80
	s_nop 0
	v_mul_f32_e32 v80, 0xc1000000, v80
	v_mul_f32_e32 v80, v139, v80
	v_mul_f32_e32 v81, 0x3fb8aa3b, v80
	v_exp_f32_e32 v81, v81
	ds_write_b32 v150, v81 offset:53052
	v_add_f32_e32 v81, v80, v80
	v_cmp_nlt_f32_e32 vcc, s65, v81
	s_and_saveexec_b64 s[6:7], vcc
	s_xor_b64 s[6:7], exec, s[6:7]
	v_mul_f32_e32 v80, 0x3fb8aa3b, v81
	v_exp_f32_e32 v80, v80
	s_nop 0
	v_sub_f32_e32 v80, 1.0, v80
	s_andn2_saveexec_b64 s[6:7], s[6:7]
	v_fmamk_f32 v80, v81, 0x39500d01, v101
	v_fmaak_f32 v80, v81, v80, 0x3c088889
	v_fmaak_f32 v80, v81, v80, 0x3d2aaaab
	v_fmaak_f32 v80, v81, v80, 0x3e2aaaab
	v_fma_f32 v80, v81, v80, 0.5
	v_fma_f32 v80, v81, v80, 1.0
	v_mul_f32_e64 v80, v80, -v81
	s_or_b64 exec, exec, s[6:7]
	v_add_f32_e32 v81, v119, v83
	v_mul_f32_e32 v81, 0xbfb8aa3b, v81
	v_exp_f32_e32 v81, v81
	ds_read_b32 v82, v150 offset:36412
	v_sqrt_f32_e32 v80, v80
	v_add_u32_e32 v97, 0xcc00, v155
	v_add_f32_e32 v81, 1.0, v81
	v_rcp_f32_e32 v81, v81
	v_add_u32_e32 v182, 0xd000, v155
	v_lshl_or_b32 v106, s92, 6, v98
	s_andn2_b64 vcc, exec, s[0:1]
	s_waitcnt lgkmcnt(0)
	v_mul_f32_e32 v81, v81, v82
	v_mul_f32_e32 v80, v80, v81
	ds_write_b32 v154, v80
	s_waitcnt lgkmcnt(0)
	s_barrier
	ds_read2_b32 v[80:81], v97 offset0:12 offset1:77
	ds_read2_b32 v[82:83], v97 offset0:142 offset1:207
	ds_read_b32 v92, v156
	ds_read_b32 v90, v157
	ds_read_b32 v88, v158
	ds_read_b32 v86, v159
	ds_read_b32 v84, v161
	ds_read_b32 v183, v162
	ds_read_b32 v95, v163
	ds_read_b32 v94, v164
	s_waitcnt lgkmcnt(7)
	v_fmac_f32_e32 v92, 0, v80
	s_waitcnt lgkmcnt(6)
	v_fmac_f32_e32 v90, v92, v81
	v_mul_f32_e32 v93, v80, v81
	ds_read2_b32 v[104:105], v182 offset0:16 offset1:81
	s_waitcnt lgkmcnt(6)
	v_fmac_f32_e32 v88, v90, v82
	v_mul_f32_e32 v91, v93, v82
	s_waitcnt lgkmcnt(5)
	v_fmac_f32_e32 v86, v88, v83
	v_mul_f32_e32 v89, v91, v83
	ds_read2_b32 v[82:83], v182 offset0:146 offset1:211
	s_waitcnt lgkmcnt(1)
	v_mul_f32_e32 v87, v89, v104
	v_fmac_f32_e32 v84, v86, v104
	v_mul_f32_e32 v85, v87, v105
	v_fmac_f32_e32 v183, v84, v105
	s_waitcnt lgkmcnt(0)
	v_mul_f32_e32 v81, v85, v82
	v_fmac_f32_e32 v95, v183, v82
	v_mul_f32_e32 v107, v81, v83
	v_fmac_f32_e32 v94, v95, v83
	ds_write_b32 v165, v107
	ds_write_b32 v166, v94
	s_waitcnt lgkmcnt(0)
	s_barrier
	v_lshl_add_u32 v82, v106, 2, v109
	ds_read_b32 v83, v82
	ds_read_b32 v216, v168
	ds_read_b32 v217, v167
	ds_read_b32 v218, v170
	ds_read_b32 v219, v169
	ds_read_b32 v220, v172
	ds_read_b32 v221, v171
	ds_read_b32 v222, v174
	ds_read_b32 v223, v173
	ds_read_b32 v224, v176
	ds_read_b32 v225, v175
	ds_read_b32 v226, v178
	ds_read_b32 v227, v177
	ds_read_b32 v228, v180
	ds_read_b32 v229, v179
	v_cndmask_b32_e64 v82, 0, 1, s[0:1]
	v_cmp_ne_u32_e64 s[6:7], 1, v82
	s_cbranch_vccnz .LBB0_589
	s_waitcnt lgkmcnt(0)
	v_fma_f32 v83, v83, v216, v217
.LBB0_589:
	v_cndmask_b32_e64 v82, 0, 1, s[24:25]
	v_cmp_ne_u32_e64 s[8:9], 1, v82
	s_andn2_b64 vcc, exec, s[24:25]
	s_cbranch_vccnz .LBB0_606
	s_waitcnt lgkmcnt(0)
	v_fma_f32 v83, v83, v218, v219
	v_cndmask_b32_e64 v82, 0, 1, s[26:27]
	v_cmp_ne_u32_e64 s[10:11], 1, v82
	s_andn2_b64 vcc, exec, s[26:27]
	s_cbranch_vccz .LBB0_607

; __device__ __forceinline__ void rglru_item8(const Params& p, unsigned char* lds, int item) {
;     ...
;     { float hin = hst[cur * 64 + j];
; #pragma unroll
;       for (int sI = 0; sI < 7; ++sI) if (sI < seg) hin = segP[sI * 64 + j] * hin + segL[sI * 64 + j];
.LBB0_592:
	s_waitcnt lgkmcnt(0)
	v_fma_f32 v83, v83, v222, v223
	v_cndmask_b32_e64 v82, 0, 1, s[30:31]
	v_cmp_ne_u32_e64 s[14:15], 1, v82
	s_andn2_b64 vcc, exec, s[30:31]
	s_cbranch_vccz .LBB0_609

; __device__ __forceinline__ void rglru_item8(const Params& p, unsigned char* lds, int item) {
;     ...
;     { float hin = hst[cur * 64 + j];
; #pragma unroll
;       for (int sI = 0; sI < 7; ++sI) if (sI < seg) hin = segP[sI * 64 + j] * hin + segL[sI * 64 + j];
.LBB0_594:
	s_waitcnt lgkmcnt(0)
	v_fma_f32 v83, v83, v226, v227
	v_cndmask_b32_e64 v82, 0, 1, s[36:37]
	v_cmp_ne_u32_e64 s[18:19], 1, v82
	s_andn2_b64 vcc, exec, s[36:37]
	s_cbranch_vccz .LBB0_611

; __device__ __forceinline__ void rglru_item8(const Params& p, unsigned char* lds, int item) {
;     ...
;     { float hin = hst[cur * 64 + j];
; #pragma unroll
;       for (int sI = 0; sI < 7; ++sI) if (sI < seg) hin = segP[sI * 64 + j] * hin + segL[sI * 64 + j];
.LBB0_607:
	s_waitcnt lgkmcnt(0)
	v_fma_f32 v83, v83, v220, v221
	v_cndmask_b32_e64 v82, 0, 1, s[28:29]
	v_cmp_ne_u32_e64 s[12:13], 1, v82
	s_andn2_b64 vcc, exec, s[28:29]
	s_cbranch_vccz .LBB0_592

; __device__ __forceinline__ void rglru_item8(const Params& p, unsigned char* lds, int item) {
;     ...
;     { float hin = hst[cur * 64 + j];
; #pragma unroll
;       for (int sI = 0; sI < 7; ++sI) if (sI < seg) hin = segP[sI * 64 + j] * hin + segL[sI * 64 + j];
.LBB0_609:
	s_waitcnt lgkmcnt(0)
	v_fma_f32 v83, v83, v224, v225
	v_cndmask_b32_e64 v82, 0, 1, s[34:35]
	v_cmp_ne_u32_e64 s[16:17], 1, v82
	s_andn2_b64 vcc, exec, s[34:35]
	s_cbranch_vccz .LBB0_594

; __device__ __forceinline__ void rglru_item8(const Params& p, unsigned char* lds, int item) {
;     ...
;     { float hin = hst[cur * 64 + j];
; #pragma unroll
;       for (int sI = 0; sI < 7; ++sI) if (sI < seg) hin = segP[sI * 64 + j] * hin + segL[sI * 64 + j];
; #pragma unroll
;       for (int k = 0; k < 8; ++k) {
;         const float hv = Lk[k] + Pk[k] * hin; const int t = 64 * ti + 8 * seg + k;
.LBB0_611:
	s_waitcnt lgkmcnt(0)
	v_fma_f32 v83, v83, v228, v229
	s_add_i32 s33, s74, s75
	s_cmpk_gt_i32 s33, 0x100f
	v_lshlrev_b32_e32 v104, 1, v98
	s_cbranch_scc0 .LBB0_596

; DEVI float sigmoidf_(float x) { return __builtin_amdgcn_rcpf(1.0f + __builtin_amdgcn_exp2f(-x * LOG2E)); }
; #define MFMA(a, b, c) __builtin_amdgcn_mfma_f32_16x16x32_bf16((a), (b), (c), 0, 0, 0)
; __device__ __forceinline__ void rglru_item8(const Params& p, unsigned char* lds, int item) {
;     ...
;       for (int kk = 0; kk < 4; ++kk) { const bf16x8 ax = *(const bf16x8*)(xcA + (16 * tt + fr) * 136 + 32 * kk + 8 * fq);
; #pragma unroll
;         for (int nt = 0; nt < 2; ++nt) { R[nt] = MFMA(ax, wa[nt][kk], R[nt]); I[nt] = MFMA(ax, wx[nt][kk], I[nt]); } }
; #pragma unroll
;       for (int nt = 0; nt < 2; ++nt)
; #pragma unroll
;         for (int r = 0; r < 4; ++r) {
;           const int t = 16 * tt + 4 * fq + r, jl = jh * 32 + 16 * nt + fr;
;           const float rg = sigmoidf_(R[nt][r] + ba[nt]), ig = sigmoidf_(I[nt][r] + bx[nt]);
;           const float la = -8.0f * rg * sp[nt];
;           aS[t * 65 + jl] = __builtin_amdgcn_exp2f(la * LOG2E);
;           const float x2 = 2.0f * la, om = x2 > -0.25f ? neg_expm1_small(x2) : 1.0f - __builtin_amdgcn_exp2f(x2 * LOG2E);
;           uS[t * 65 + jl] = __builtin_amdgcn_sqrtf(om) * (ig * xcF[t * 65 + jl]);
;         }
.LBB0_649:
	ds_read_b128 v[80:83], v103 offset:18224
	ds_read_b128 v[184:187], v103 offset:18288
	s_waitcnt lgkmcnt(1)
	v_mfma_f32_16x16x32_bf16 v[84:87], v[80:83], v[0:3], 0
	v_mfma_f32_16x16x32_bf16 v[88:91], v[80:83], v[8:11], 0
	v_mfma_f32_16x16x32_bf16 v[92:95], v[80:83], v[32:35], 0
	v_mfma_f32_16x16x32_bf16 v[80:83], v[80:83], v[40:43], 0
	s_waitcnt lgkmcnt(0)
	v_mfma_f32_16x16x32_bf16 v[84:87], v[184:187], v[4:7], v[84:87]
	v_mfma_f32_16x16x32_bf16 v[88:91], v[184:187], v[12:15], v[88:91]
	v_mfma_f32_16x16x32_bf16 v[92:95], v[184:187], v[36:39], v[92:95]
	v_mfma_f32_16x16x32_bf16 v[80:83], v[184:187], v[44:47], v[80:83]
	ds_read_b128 v[184:187], v103 offset:18352
	s_waitcnt lgkmcnt(0)
	v_mfma_f32_16x16x32_bf16 v[84:87], v[184:187], v[16:19], v[84:87]
	v_mfma_f32_16x16x32_bf16 v[88:91], v[184:187], v[24:27], v[88:91]
	v_mfma_f32_16x16x32_bf16 v[188:191], v[184:187], v[48:51], v[92:95]
	v_mfma_f32_16x16x32_bf16 v[80:83], v[184:187], v[56:59], v[80:83]
	ds_read_b128 v[184:187], v103 offset:18416
	s_waitcnt lgkmcnt(0)
	v_mfma_f32_16x16x32_bf16 v[92:95], v[184:187], v[20:23], v[84:87]
	s_nop 7
	v_add_f32_e32 v92, v116, v92
	v_mul_f32_e32 v92, 0xbfb8aa3b, v92
	v_exp_f32_e32 v92, v92
	v_mfma_f32_16x16x32_bf16 v[88:91], v[184:187], v[28:31], v[88:91]
	v_add_f32_e32 v92, 1.0, v92
	v_rcp_f32_e32 v92, v92
	v_mfma_f32_16x16x32_bf16 v[84:87], v[184:187], v[52:55], v[188:191]
	v_mul_f32_e32 v92, 0xc1000000, v92
	v_mul_f32_e32 v92, v137, v92
	v_mul_f32_e32 v105, 0x3fb8aa3b, v92
	v_exp_f32_e32 v105, v105
	v_mfma_f32_16x16x32_bf16 v[80:83], v[184:187], v[60:63], v[80:83]
	ds_write_b32 v145, v105 offset:52272
	v_add_f32_e32 v105, v92, v92
	v_cmp_nlt_f32_e32 vcc, s65, v105
	s_and_saveexec_b64 s[42:43], vcc
	s_xor_b64 s[42:43], exec, s[42:43]
	v_mul_f32_e32 v92, 0x3fb8aa3b, v105
	v_exp_f32_e32 v92, v92
	s_nop 0
	v_sub_f32_e32 v92, 1.0, v92
	s_andn2_saveexec_b64 s[42:43], s[42:43]
	v_fmamk_f32 v92, v105, 0x39500d01, v101
	v_fmaak_f32 v92, v105, v92, 0x3c088889
	v_fmaak_f32 v92, v105, v92, 0x3d2aaaab
	v_fmaak_f32 v92, v105, v92, 0x3e2aaaab
	v_fma_f32 v92, v105, v92, 0.5
	v_fma_f32 v92, v105, v92, 1.0
	v_mul_f32_e64 v92, v92, -v105
	s_or_b64 exec, exec, s[42:43]
	v_add_f32_e32 v88, v118, v88
	v_mul_f32_e32 v88, 0xbfb8aa3b, v88
	v_exp_f32_e32 v88, v88
	ds_read_b32 v105, v145 offset:35632
	v_sqrt_f32_e32 v92, v92
	v_add_f32_e32 v88, 1.0, v88
	v_rcp_f32_e32 v88, v88
	s_waitcnt lgkmcnt(0)
	v_mul_f32_e32 v88, v88, v105
	v_mul_f32_e32 v88, v92, v88
	ds_write_b32 v146, v88
	v_add_f32_e32 v88, v116, v93
	v_mul_f32_e32 v88, 0xbfb8aa3b, v88
	v_exp_f32_e32 v88, v88
	s_nop 0
	v_add_f32_e32 v88, 1.0, v88
	v_rcp_f32_e32 v88, v88
	s_nop 0
	v_mul_f32_e32 v88, 0xc1000000, v88
	v_mul_f32_e32 v88, v137, v88
	v_mul_f32_e32 v92, 0x3fb8aa3b, v88
	v_exp_f32_e32 v92, v92
	ds_write_b32 v145, v92 offset:52532
	v_add_f32_e32 v92, v88, v88
	v_cmp_nlt_f32_e32 vcc, s65, v92
	s_and_saveexec_b64 s[42:43], vcc
	s_xor_b64 s[42:43], exec, s[42:43]
	v_mul_f32_e32 v88, 0x3fb8aa3b, v92
	v_exp_f32_e32 v88, v88
	s_nop 0
	v_sub_f32_e32 v88, 1.0, v88
	s_andn2_saveexec_b64 s[42:43], s[42:43]
	v_fmamk_f32 v88, v92, 0x39500d01, v101
	v_fmaak_f32 v88, v92, v88, 0x3c088889
	v_fmaak_f32 v88, v92, v88, 0x3d2aaaab
	v_fmaak_f32 v88, v92, v88, 0x3e2aaaab
	v_fma_f32 v88, v92, v88, 0.5
	v_fma_f32 v88, v92, v88, 1.0
	v_mul_f32_e64 v88, v88, -v92
	s_or_b64 exec, exec, s[42:43]
	v_add_f32_e32 v89, v118, v89
	v_mul_f32_e32 v89, 0xbfb8aa3b, v89
	v_exp_f32_e32 v89, v89
	ds_read_b32 v92, v145 offset:35892
	v_sqrt_f32_e32 v88, v88
	v_add_f32_e32 v89, 1.0, v89
	v_rcp_f32_e32 v89, v89
	s_waitcnt lgkmcnt(0)
	v_mul_f32_e32 v89, v89, v92
	v_mul_f32_e32 v88, v88, v89
	ds_write_b32 v147, v88
	v_add_f32_e32 v88, v116, v94
	v_mul_f32_e32 v88, 0xbfb8aa3b, v88
	v_exp_f32_e32 v88, v88
	s_nop 0
	v_add_f32_e32 v88, 1.0, v88
	v_rcp_f32_e32 v88, v88
	s_nop 0
	v_mul_f32_e32 v88, 0xc1000000, v88
	v_mul_f32_e32 v88, v137, v88
	v_mul_f32_e32 v89, 0x3fb8aa3b, v88
	v_exp_f32_e32 v89, v89
	ds_write_b32 v145, v89 offset:52792
	v_add_f32_e32 v89, v88, v88
	v_cmp_nlt_f32_e32 vcc, s65, v89
	s_and_saveexec_b64 s[42:43], vcc
	s_xor_b64 s[42:43], exec, s[42:43]
	v_mul_f32_e32 v88, 0x3fb8aa3b, v89
	v_exp_f32_e32 v88, v88
	s_nop 0
	v_sub_f32_e32 v88, 1.0, v88
	s_andn2_saveexec_b64 s[42:43], s[42:43]
	v_fmamk_f32 v88, v89, 0x39500d01, v101
	v_fmaak_f32 v88, v89, v88, 0x3c088889
	v_fmaak_f32 v88, v89, v88, 0x3d2aaaab
	v_fmaak_f32 v88, v89, v88, 0x3e2aaaab
	v_fma_f32 v88, v89, v88, 0.5
	v_fma_f32 v88, v89, v88, 1.0
	v_mul_f32_e64 v88, v88, -v89
	s_or_b64 exec, exec, s[42:43]
	v_add_f32_e32 v89, v118, v90
	v_mul_f32_e32 v89, 0xbfb8aa3b, v89
	v_exp_f32_e32 v89, v89
	ds_read_b32 v90, v145 offset:36152
	v_sqrt_f32_e32 v88, v88
	v_add_f32_e32 v89, 1.0, v89
	v_rcp_f32_e32 v89, v89
	s_waitcnt lgkmcnt(0)
	v_mul_f32_e32 v89, v89, v90
	v_mul_f32_e32 v88, v88, v89
	ds_write_b32 v148, v88
	v_add_f32_e32 v88, v116, v95
	v_mul_f32_e32 v88, 0xbfb8aa3b, v88
	v_exp_f32_e32 v88, v88
	s_nop 0
	v_add_f32_e32 v88, 1.0, v88
	v_rcp_f32_e32 v88, v88
	s_nop 0
	v_mul_f32_e32 v88, 0xc1000000, v88
	v_mul_f32_e32 v88, v137, v88
	v_mul_f32_e32 v89, 0x3fb8aa3b, v88
	v_exp_f32_e32 v89, v89
	ds_write_b32 v145, v89 offset:53052
	v_add_f32_e32 v89, v88, v88
	v_cmp_nlt_f32_e32 vcc, s65, v89
	s_and_saveexec_b64 s[42:43], vcc
	s_xor_b64 s[42:43], exec, s[42:43]
	v_mul_f32_e32 v88, 0x3fb8aa3b, v89
	v_exp_f32_e32 v88, v88
	s_nop 0
	v_sub_f32_e32 v88, 1.0, v88
	s_andn2_saveexec_b64 s[42:43], s[42:43]
	v_fmamk_f32 v88, v89, 0x39500d01, v101
	v_fmaak_f32 v88, v89, v88, 0x3c088889
	v_fmaak_f32 v88, v89, v88, 0x3d2aaaab
	v_fmaak_f32 v88, v89, v88, 0x3e2aaaab
	v_fma_f32 v88, v89, v88, 0.5
	v_fma_f32 v88, v89, v88, 1.0
	v_mul_f32_e64 v88, v88, -v89
	s_or_b64 exec, exec, s[42:43]
	v_add_f32_e32 v89, v118, v91
	v_add_f32_e32 v84, v117, v84
	v_mul_f32_e32 v89, 0xbfb8aa3b, v89
	v_mul_f32_e32 v84, 0xbfb8aa3b, v84
	v_exp_f32_e32 v89, v89
	v_exp_f32_e32 v84, v84
	ds_read_b32 v90, v145 offset:36412
	v_sqrt_f32_e32 v88, v88
	v_add_f32_e32 v89, 1.0, v89
	v_add_f32_e32 v84, 1.0, v84
	v_rcp_f32_e32 v89, v89
	v_rcp_f32_e32 v84, v84
	s_waitcnt lgkmcnt(0)
; DEVI float sigmoidf_(float x) { return __builtin_amdgcn_rcpf(1.0f + __builtin_amdgcn_exp2f(-x * LOG2E)); }
; #define LBAR() do { asm volatile("s_waitcnt lgkmcnt(0)" ::: "memory"); __builtin_amdgcn_s_barrier(); asm volatile("" ::: "memory"); } while (0)
; __device__ __forceinline__ void rglru_item8(const Params& p, unsigned char* lds, int item) {
;     ...
;         for (int r = 0; r < 4; ++r) {
;           const int t = 16 * tt + 4 * fq + r, jl = jh * 32 + 16 * nt + fr;
;           const float rg = sigmoidf_(R[nt][r] + ba[nt]), ig = sigmoidf_(I[nt][r] + bx[nt]);
;           const float la = -8.0f * rg * sp[nt];
;           aS[t * 65 + jl] = __builtin_amdgcn_exp2f(la * LOG2E);
;           const float x2 = 2.0f * la, om = x2 > -0.25f ? neg_expm1_small(x2) : 1.0f - __builtin_amdgcn_exp2f(x2 * LOG2E);
;           uS[t * 65 + jl] = __builtin_amdgcn_sqrtf(om) * (ig * xcF[t * 65 + jl]);
;         }
;     }
;     LBAR();
;     const int j = lane, seg = w;
;     float Lk[8], Pk[8];
;     { float P = 1.f, L = 0.f;
; #pragma unroll
;       for (int k = 0; k < 8; ++k) { const float a = aS[(8 * seg + k) * 65 + j], u = uS[(8 * seg + k) * 65 + j]; L = a * L + u; P = a * P; Lk[k] = L; Pk[k] = P; }
;       segP[seg * 64 + j] = P; segL[seg * 64 + j] = L; }
;     LBAR();
;     { float hin = hst[cur * 64 + j];
; #pragma unroll
;       for (int sI = 0; sI < 7; ++sI) if (sI < seg) hin = segP[sI * 64 + j] * hin + segL[sI * 64 + j];
	v_mul_f32_e32 v89, v89, v90
	v_mul_f32_e32 v84, 0xc1000000, v84
	v_mul_f32_e32 v88, v88, v89
	v_mul_f32_e32 v84, v139, v84
	ds_write_b32 v149, v88
	v_mul_f32_e32 v88, 0x3fb8aa3b, v84
	v_exp_f32_e32 v88, v88
	ds_write_b32 v145, v88 offset:52336
	v_add_f32_e32 v88, v84, v84
	v_cmp_nlt_f32_e32 vcc, s65, v88
	s_and_saveexec_b64 s[42:43], vcc
	s_xor_b64 s[42:43], exec, s[42:43]
	v_mul_f32_e32 v84, 0x3fb8aa3b, v88
	v_exp_f32_e32 v84, v84
	s_nop 0
	v_sub_f32_e32 v84, 1.0, v84
	s_andn2_saveexec_b64 s[42:43], s[42:43]
	v_fmamk_f32 v84, v88, 0x39500d01, v101
	v_fmaak_f32 v84, v88, v84, 0x3c088889
	v_fmaak_f32 v84, v88, v84, 0x3d2aaaab
	v_fmaak_f32 v84, v88, v84, 0x3e2aaaab
	v_fma_f32 v84, v88, v84, 0.5
	v_fma_f32 v84, v88, v84, 1.0
	v_mul_f32_e64 v84, v84, -v88
	s_or_b64 exec, exec, s[42:43]
	v_add_f32_e32 v80, v119, v80
	v_mul_f32_e32 v80, 0xbfb8aa3b, v80
	v_exp_f32_e32 v80, v80
	ds_read_b32 v88, v145 offset:35696
	v_sqrt_f32_e32 v84, v84
	v_add_f32_e32 v80, 1.0, v80
	v_rcp_f32_e32 v80, v80
	s_waitcnt lgkmcnt(0)
	v_mul_f32_e32 v80, v80, v88
	v_mul_f32_e32 v80, v84, v80
	ds_write_b32 v151, v80
	v_add_f32_e32 v80, v117, v85
	v_mul_f32_e32 v80, 0xbfb8aa3b, v80
	v_exp_f32_e32 v80, v80
	s_nop 0
	v_add_f32_e32 v80, 1.0, v80
	v_rcp_f32_e32 v80, v80
	s_nop 0
	v_mul_f32_e32 v80, 0xc1000000, v80
	v_mul_f32_e32 v80, v139, v80
	v_mul_f32_e32 v84, 0x3fb8aa3b, v80
	v_exp_f32_e32 v84, v84
	ds_write_b32 v150, v84 offset:52532
	v_add_f32_e32 v84, v80, v80
	v_cmp_nlt_f32_e32 vcc, s65, v84
	s_and_saveexec_b64 s[42:43], vcc
	s_xor_b64 s[42:43], exec, s[42:43]
	v_mul_f32_e32 v80, 0x3fb8aa3b, v84
	v_exp_f32_e32 v80, v80
	s_nop 0
	v_sub_f32_e32 v80, 1.0, v80
	s_andn2_saveexec_b64 s[42:43], s[42:43]
	v_fmamk_f32 v80, v84, 0x39500d01, v101
	v_fmaak_f32 v80, v84, v80, 0x3c088889
	v_fmaak_f32 v80, v84, v80, 0x3d2aaaab
	v_fmaak_f32 v80, v84, v80, 0x3e2aaaab
	v_fma_f32 v80, v84, v80, 0.5
	v_fma_f32 v80, v84, v80, 1.0
	v_mul_f32_e64 v80, v80, -v84
	s_or_b64 exec, exec, s[42:43]
	v_add_f32_e32 v81, v119, v81
	v_mul_f32_e32 v81, 0xbfb8aa3b, v81
	v_exp_f32_e32 v81, v81
	ds_read_b32 v84, v150 offset:35892
	v_sqrt_f32_e32 v80, v80
	v_add_f32_e32 v81, 1.0, v81
	v_rcp_f32_e32 v81, v81
	s_waitcnt lgkmcnt(0)
	v_mul_f32_e32 v81, v81, v84
	v_mul_f32_e32 v80, v80, v81
	ds_write_b32 v152, v80
	v_add_f32_e32 v80, v117, v86
	v_mul_f32_e32 v80, 0xbfb8aa3b, v80
	v_exp_f32_e32 v80, v80
	s_nop 0
	v_add_f32_e32 v80, 1.0, v80
	v_rcp_f32_e32 v80, v80
	s_nop 0
	v_mul_f32_e32 v80, 0xc1000000, v80
	v_mul_f32_e32 v80, v139, v80
	v_mul_f32_e32 v81, 0x3fb8aa3b, v80
	v_exp_f32_e32 v81, v81
	ds_write_b32 v150, v81 offset:52792
	v_add_f32_e32 v81, v80, v80
	v_cmp_nlt_f32_e32 vcc, s65, v81
	s_and_saveexec_b64 s[42:43], vcc
	s_xor_b64 s[42:43], exec, s[42:43]
	v_mul_f32_e32 v80, 0x3fb8aa3b, v81
	v_exp_f32_e32 v80, v80
	s_nop 0
	v_sub_f32_e32 v80, 1.0, v80
	s_andn2_saveexec_b64 s[42:43], s[42:43]
	v_fmamk_f32 v80, v81, 0x39500d01, v101
	v_fmaak_f32 v80, v81, v80, 0x3c088889
	v_fmaak_f32 v80, v81, v80, 0x3d2aaaab
	v_fmaak_f32 v80, v81, v80, 0x3e2aaaab
	v_fma_f32 v80, v81, v80, 0.5
	v_fma_f32 v80, v81, v80, 1.0
	v_mul_f32_e64 v80, v80, -v81
	s_or_b64 exec, exec, s[42:43]
	v_add_f32_e32 v81, v119, v82
	v_mul_f32_e32 v81, 0xbfb8aa3b, v81
	v_exp_f32_e32 v81, v81
	ds_read_b32 v82, v150 offset:36152
	v_sqrt_f32_e32 v80, v80
	v_add_f32_e32 v81, 1.0, v81
	v_rcp_f32_e32 v81, v81
	s_waitcnt lgkmcnt(0)
	v_mul_f32_e32 v81, v81, v82
	v_mul_f32_e32 v80, v80, v81
	ds_write_b32 v153, v80
	v_add_f32_e32 v80, v117, v87
	v_mul_f32_e32 v80, 0xbfb8aa3b, v80
	v_exp_f32_e32 v80, v80
	s_nop 0
	v_add_f32_e32 v80, 1.0, v80
	v_rcp_f32_e32 v80, v80
	s_nop 0
	v_mul_f32_e32 v80, 0xc1000000, v80
	v_mul_f32_e32 v80, v139, v80
	v_mul_f32_e32 v81, 0x3fb8aa3b, v80
	v_exp_f32_e32 v81, v81
	ds_write_b32 v150, v81 offset:53052
	v_add_f32_e32 v81, v80, v80
	v_cmp_nlt_f32_e32 vcc, s65, v81
	s_and_saveexec_b64 s[42:43], vcc
	s_xor_b64 s[42:43], exec, s[42:43]
	v_mul_f32_e32 v80, 0x3fb8aa3b, v81
	v_exp_f32_e32 v80, v80
	s_nop 0
	v_sub_f32_e32 v80, 1.0, v80
	s_andn2_saveexec_b64 s[42:43], s[42:43]
	v_fmamk_f32 v80, v81, 0x39500d01, v101
	v_fmaak_f32 v80, v81, v80, 0x3c088889
	v_fmaak_f32 v80, v81, v80, 0x3d2aaaab
	v_fmaak_f32 v80, v81, v80, 0x3e2aaaab
	v_fma_f32 v80, v81, v80, 0.5
	v_fma_f32 v80, v81, v80, 1.0
	v_mul_f32_e64 v80, v80, -v81
	s_or_b64 exec, exec, s[42:43]
	v_add_f32_e32 v81, v119, v83
	v_mul_f32_e32 v81, 0xbfb8aa3b, v81
	v_exp_f32_e32 v81, v81
	ds_read_b32 v82, v150 offset:36412
	v_sqrt_f32_e32 v80, v80
	v_lshl_or_b32 v106, s62, 6, v98
	v_add_f32_e32 v81, 1.0, v81
	v_rcp_f32_e32 v81, v81
	s_and_b64 vcc, exec, s[6:7]
	s_waitcnt lgkmcnt(0)
	v_mul_f32_e32 v81, v81, v82
	v_mul_f32_e32 v80, v80, v81
	ds_write_b32 v154, v80
	s_waitcnt lgkmcnt(0)
	s_barrier
	ds_read2_b32 v[80:81], v97 offset0:12 offset1:77
	ds_read2_b32 v[82:83], v97 offset0:142 offset1:207
	ds_read_b32 v92, v156
	ds_read_b32 v90, v157
	ds_read_b32 v88, v158
	ds_read_b32 v86, v159
	ds_read_b32 v84, v161
	ds_read_b32 v107, v162
	ds_read_b32 v95, v163
	ds_read_b32 v94, v164
	s_waitcnt lgkmcnt(7)
	v_fmac_f32_e32 v92, 0, v80
	s_waitcnt lgkmcnt(6)
	v_fmac_f32_e32 v90, v92, v81
	v_mul_f32_e32 v93, v80, v81
	ds_read2_b32 v[184:185], v182 offset0:16 offset1:81
	s_waitcnt lgkmcnt(6)
	v_fmac_f32_e32 v88, v90, v82
	v_mul_f32_e32 v91, v93, v82
	s_waitcnt lgkmcnt(5)
	v_fmac_f32_e32 v86, v88, v83
	v_mul_f32_e32 v89, v91, v83
	ds_read2_b32 v[82:83], v182 offset0:146 offset1:211
	s_waitcnt lgkmcnt(1)
	v_mul_f32_e32 v87, v89, v184
	v_fmac_f32_e32 v84, v86, v184
	v_mul_f32_e32 v85, v87, v185
	v_fmac_f32_e32 v107, v84, v185
	s_waitcnt lgkmcnt(0)
	v_mul_f32_e32 v81, v85, v82
	v_fmac_f32_e32 v95, v107, v82
	v_mul_f32_e32 v97, v81, v83
	v_fmac_f32_e32 v94, v95, v83
	ds_write_b32 v165, v97
	ds_write_b32 v166, v94
	s_waitcnt lgkmcnt(0)
	s_barrier
	v_lshl_add_u32 v82, v106, 2, v109
	ds_read_b32 v83, v82
	ds_read_b32 v216, v168
	ds_read_b32 v217, v167
	ds_read_b32 v218, v170
	ds_read_b32 v219, v169
	ds_read_b32 v220, v172
	ds_read_b32 v221, v171
	ds_read_b32 v222, v174
	ds_read_b32 v223, v173
	ds_read_b32 v224, v176
	ds_read_b32 v225, v175
	ds_read_b32 v226, v178
	ds_read_b32 v227, v177
	ds_read_b32 v228, v180
	ds_read_b32 v229, v179
	s_cbranch_vccnz .LBB0_683
	s_waitcnt lgkmcnt(0)
	v_fma_f32 v83, v83, v216, v217
.LBB0_683:
	s_and_b64 vcc, exec, s[8:9]
	s_cbranch_vccnz .LBB0_699
	s_waitcnt lgkmcnt(0)
	v_fma_f32 v83, v83, v218, v219
	s_and_b64 vcc, exec, s[10:11]
	s_cbranch_vccz .LBB0_700

; __device__ __forceinline__ void rglru_item8(const Params& p, unsigned char* lds, int item) {
;     ...
;     { float hin = hst[cur * 64 + j];
; #pragma unroll
;       for (int sI = 0; sI < 7; ++sI) if (sI < seg) hin = segP[sI * 64 + j] * hin + segL[sI * 64 + j];
.LBB0_686:
	s_waitcnt lgkmcnt(0)
	v_fma_f32 v83, v83, v222, v223
	s_and_b64 vcc, exec, s[14:15]
	s_cbranch_vccz .LBB0_702

; __device__ __forceinline__ void rglru_item8(const Params& p, unsigned char* lds, int item) {
;     ...
;     { float hin = hst[cur * 64 + j];
; #pragma unroll
;       for (int sI = 0; sI < 7; ++sI) if (sI < seg) hin = segP[sI * 64 + j] * hin + segL[sI * 64 + j];
.LBB0_688:
	s_waitcnt lgkmcnt(0)
	v_fma_f32 v83, v83, v226, v227
	s_and_b64 vcc, exec, s[18:19]
	s_cbranch_vccz .LBB0_704

; __device__ __forceinline__ void rglru_item8(const Params& p, unsigned char* lds, int item) {
;     ...
;     { float hin = hst[cur * 64 + j];
; #pragma unroll
;       for (int sI = 0; sI < 7; ++sI) if (sI < seg) hin = segP[sI * 64 + j] * hin + segL[sI * 64 + j];
.LBB0_700:
	s_waitcnt lgkmcnt(0)
	v_fma_f32 v83, v83, v220, v221
	s_and_b64 vcc, exec, s[12:13]
	s_cbranch_vccz .LBB0_686

; __device__ __forceinline__ void rglru_item8(const Params& p, unsigned char* lds, int item) {
;     ...
;     { float hin = hst[cur * 64 + j];
; #pragma unroll
;       for (int sI = 0; sI < 7; ++sI) if (sI < seg) hin = segP[sI * 64 + j] * hin + segL[sI * 64 + j];
.LBB0_702:
	s_waitcnt lgkmcnt(0)
	v_fma_f32 v83, v83, v224, v225
	s_and_b64 vcc, exec, s[16:17]
	s_cbranch_vccz .LBB0_688

; __device__ __forceinline__ void rglru_item8(const Params& p, unsigned char* lds, int item) {
;     ...
;     { float hin = hst[cur * 64 + j];
; #pragma unroll
;       for (int sI = 0; sI < 7; ++sI) if (sI < seg) hin = segP[sI * 64 + j] * hin + segL[sI * 64 + j];
; #pragma unroll
;       for (int k = 0; k < 8; ++k) {
;         const float hv = Lk[k] + Pk[k] * hin; const int t = 64 * ti + 8 * seg + k;
.LBB0_704:
	s_waitcnt lgkmcnt(0)
	v_fma_f32 v83, v83, v228, v229
	s_add_i32 s6, s33, 64
	s_cmpk_gt_i32 s6, 0x100f
	s_cbranch_scc0 .LBB0_690
